# retention mixer loop: static s_setprio 1 for waves 4-7
# baseline (speedup 1.0000x reference)
; #define LAS __attribute__((address_space(3)))
; __device__ __forceinline__ unsigned cvt_pk_bf16(float lo, float hi) { unsigned r; asm("v_cvt_pk_bf16_f32 %0, %1, %2" : "=v"(r) : "v"(lo), "v"(hi)); return r; }
; __device__ __forceinline__ float exp2_(float x) { return __builtin_amdgcn_exp2f(x); }
; #define LDS_BARRIER() do { asm volatile("s_waitcnt lgkmcnt(0)" ::: "memory"); __builtin_amdgcn_s_barrier(); asm volatile("" ::: "memory"); } while (0)
; template <int DK, bool IS_A, int NDV>
; __device__ __forceinline__ void mix_stream(const Params& p, LAS unsigned char* lds, int l, int rs, int T, int h, int dir, int dvh) {
;     ...
;                 if (cp >= 32) { *(LAS u32x4*)(Kt + (2 * ci) * TP + ((sg * 16) ^ (gk << 4))) = (u32x4){kt0[0], kt0[1], kt0[2], kt0[3]};
;                                 *(LAS u32x4*)(Kt + (2 * ci + 1) * TP + ((sg * 16) ^ (gk << 4))) = (u32x4){kt1[0], kt1[1], kt1[2], kt1[3]}; }
;             }
;             if (NDV == 8 || cp < 32) {
;             *(LAS u32x4*)(Vt + (2 * cp) * TP + ((sg * 16) ^ (gk << 4))) = (u32x4){vt0[0], vt0[1], vt0[2], vt0[3]};
;             *(LAS u32x4*)(Vt + (2 * cp + 1) * TP + ((sg * 16) ^ (gk << 4))) = (u32x4){vt1[0], vt1[1], vt1[2], vt1[3]}; }
;         }
; #pragma unroll
;         for (int dki = 0; dki < 2; ++dki) { f32x4 er;
;           if (IS_A) { const int dk = (tdk0 + dki) * 16 + fq * 4; const f32x4 e = *(const LAS f32x4*)(seg + dk) + *(const LAS f32x4*)(seg + DK + dk) + *(const LAS f32x4*)(seg + 2 * DK + dk) + *(const LAS f32x4*)(seg + 3 * DK + dk);
; #pragma unroll
;               for (int j = 0; j < 4; ++j) er[j] = exp2_(fmaxf(e[j], -115.f)); }
;           else { const float e = __expf(32.0f * lg); er = (f32x4){e, e, e, e}; }
; #pragma unroll
;           for (int dvi = 0; dvi < DVW; ++dvi) { const f32x4 sv = S[dki * DVW + dvi] * er; u32x2 pk; pk.x = cvt_pk_bf16(sv[0], sv[1]); pk.y = cvt_pk_bf16(sv[2], sv[3]);
;               *(LAS u32x2*)(St + ((tdv0 + dvi) * 16 + fr) * QP + ((((tdk0 + dki) * 16 + fq * 4) * 2) ^ (gx << 4))) = pk; } }
;         if (n + 1 < N) MIX_LOAD(n + 1, par);
;         LDS_BARRIER();
.LBB0_163:
	s_or_b64 exec, exec, s[0:1]
	s_and_b64 s[0:1], vcc, exec
	s_cselect_b32 s0, s77, 0x8670000
	s_ashr_i32 s14, s13, 7
	s_lshl_b32 s42, s12, 1
	v_lshlrev_b32_e32 v30, 5, v31
	v_ashrrev_i32_e32 v34, 3, v31
	s_add_u32 s0, s68, s0
	v_and_b32_e32 v70, 0xe0, v30
	v_sub_u32_e32 v30, 63, v34
	s_addc_u32 s1, s69, 0
	v_cndmask_b32_e32 v30, v30, v34, vcc
	s_ashr_i32 s13, s13, 3
	s_lshr_b32 s10, s19, 6
	v_lshlrev_b32_e32 v30, 11, v30
	s_lshl_b32 s43, s12, 5
	s_and_b32 s11, s16, 3
	s_andn2_b32 s13, s13, 31
	s_or_b32 s60, s42, 1
	s_add_i32 s42, s19, 0xffffff80
	v_or3_b32 v30, v30, v70, s17
	s_and_b64 s[16:17], vcc, exec
	s_cselect_b32 s16, 64, s42
	s_add_i32 s16, s16, s18
	s_mul_hi_i32 s17, s16, 0x5000
	s_mulk_i32 s16, 0x5000
	s_add_u32 s16, s98, s16
	v_mov_b32_e32 v11, v177
	s_addc_u32 s17, s99, s17
	v_mov_b32_e32 v1, v177
	v_mov_b32_e32 v3, v177
	v_mov_b32_e32 v5, v177
	v_mov_b32_e32 v7, v177
	v_mov_b32_e32 v9, v177
	v_mov_b32_e32 v13, v177
	v_mov_b32_e32 v15, v177
	v_lshl_add_u64 v[36:37], s[16:17], 0, v[176:177]
	v_lshl_add_u64 v[78:79], s[16:17], 0, v[10:11]
	v_mov_b32_e32 v17, v177
	v_mov_b32_e32 v19, v177
	v_mov_b32_e32 v21, v177
	v_mov_b32_e32 v23, v177
	v_mov_b32_e32 v25, v177
	v_mov_b32_e32 v27, v177
	v_mov_b32_e32 v29, v177
	v_lshl_add_u64 v[48:49], s[16:17], 0, v[0:1]
	v_lshl_add_u64 v[50:51], s[16:17], 0, v[2:3]
	v_lshl_add_u64 v[52:53], s[16:17], 0, v[4:5]
	v_lshl_add_u64 v[54:55], s[16:17], 0, v[6:7]
	v_lshl_add_u64 v[56:57], s[16:17], 0, v[8:9]
	v_lshl_add_u64 v[80:81], s[16:17], 0, v[12:13]
	global_load_dword v72, v[36:37], off
	global_load_dword v73, v[48:49], off
	global_load_dword v74, v[50:51], off
	global_load_dword v75, v[52:53], off
	global_load_dword v76, v[54:55], off
	global_load_dword v77, v[56:57], off
	s_nop 0
	global_load_dword v78, v[78:79], off
	s_nop 0
	global_load_dword v79, v[80:81], off
	v_lshl_add_u64 v[36:37], s[16:17], 0, v[14:15]
	v_lshl_add_u64 v[48:49], s[16:17], 0, v[16:17]
	v_lshl_add_u64 v[50:51], s[16:17], 0, v[18:19]
	v_lshl_add_u64 v[52:53], s[16:17], 0, v[20:21]
	v_lshl_add_u64 v[54:55], s[16:17], 0, v[22:23]
	v_lshl_add_u64 v[56:57], s[16:17], 0, v[24:25]
	v_lshl_add_u64 v[80:81], s[16:17], 0, v[26:27]
	v_lshl_add_u64 v[86:87], s[16:17], 0, v[28:29]
	global_load_dword v82, v[36:37], off
	global_load_dword v84, v[48:49], off
	global_load_dword v88, v[50:51], off
	global_load_dword v89, v[52:53], off
	global_load_dword v90, v[54:55], off
	global_load_dword v91, v[56:57], off
	global_load_dword v92, v[80:81], off
	global_load_dword v96, v[86:87], off
	v_and_b32_e32 v95, 15, v31
	s_movk_i32 s16, 0x120
	v_lshrrev_b32_e32 v85, 4, v35
	v_mad_u32_u24 v35, v35, s16, 0
	v_lshl_or_b32 v48, s14, 4, v95
	s_movk_i32 s16, 0x90
	v_mul_lo_u32 v49, v48, s16
	v_or_b32_e32 v97, s43, v95
	v_add_u32_e32 v94, 0, v49
	v_or_b32_e32 v49, 16, v97
	v_mad_u32_u24 v55, v49, s16, 0
	v_lshl_or_b32 v49, v85, 2, s43
	s_movk_i32 s78, 0x110
	v_or_b32_e32 v51, 2, v49
	v_mul_lo_u32 v71, v34, s78
	v_mul_f32_e32 v34, 0xc2000000, v38
	v_cmp_lt_i32_e64 s[46:47], v48, v51
	v_or_b32_e32 v51, 3, v49
	v_mul_f32_e32 v34, 0x3fb8aa3b, v34
	v_cmp_lt_i32_e64 s[48:49], v48, v51
	v_or_b32_e32 v51, 17, v49
	v_add_u32_e32 v31, 4, v31
	v_exp_f32_e32 v34, v34
	v_cmp_lt_i32_e64 s[52:53], v48, v51
	v_or_b32_e32 v51, 18, v49
	v_lshrrev_b32_e32 v32, 3, v31
	v_bfe_u32 v83, v31, 3, 1
	v_or_b32_e32 v50, 16, v49
	v_cmp_lt_i32_e64 s[54:55], v48, v51
	v_or_b32_e32 v51, 19, v49
	v_bitop3_b32 v93, v32, v85, 1 bitop3:0x6c
	v_lshlrev_b32_e32 v52, 4, v83
	v_cmp_lt_i32_e64 s[42:43], v48, v49
	v_cmp_gt_i32_e64 s[44:45], v48, v49
	v_cmp_lt_i32_e64 s[50:51], v48, v50
	v_cmp_lt_i32_e64 s[56:57], v48, v51
	v_lshlrev_b32_e32 v48, 1, v49
	v_lshlrev_b32_e32 v53, 4, v93
	v_xor_b32_e32 v93, v48, v52
	v_lshlrev_b32_e32 v48, 1, v50
	v_lshlrev_b32_e32 v155, 3, v85
	v_xor_b32_e32 v106, v48, v52
	v_perm_b32 v48, v40, v39, s3
	v_perm_b32 v40, v40, v39, s23
	v_perm_b32 v49, v42, v41, s3
	v_perm_b32 v41, v42, v41, s23
	v_perm_b32 v50, v44, v43, s3
	s_waitcnt vmcnt(0)
	v_perm_b32 v51, v46, v45, s3
	v_add_u32_e32 v80, v35, v47
	v_mul_f32_e32 v39, 0, v34
	v_perm_b32 v42, v44, v43, s23
	v_perm_b32 v43, v46, v45, s23
	ds_write_b128 v80, v[48:51] offset:18432
	ds_write_b128 v80, v[40:43] offset:18576
	v_lshl_or_b32 v35, s12, 6, v155
	v_cvt_pk_bf16_f32 v40, v39, v39
	v_cvt_pk_bf16_f32 v41, v39, v39
	v_lshl_or_b32 v39, s14, 5, v95
	v_xad_u32 v35, v35, v52, 0
	v_mul_lo_u32 v39, v39, s16
	v_add_u32_e32 v81, v35, v39
	v_lshl_or_b32 v35, s60, 5, v155
	v_xad_u32 v35, v35, v52, 0
	v_add_u32_e32 v83, v35, v39
	ds_write_b64 v81, v[40:41] offset:46080
	ds_write_b64 v81, v[40:41] offset:48384
	ds_write_b64 v83, v[40:41] offset:46080
	ds_write_b64 v83, v[40:41] offset:48384
	v_mad_u32_u24 v54, v97, s16, 0
	s_waitcnt lgkmcnt(0)
	s_barrier
; template <int DK, bool IS_A, int NDV>
; __device__ __forceinline__ void mix_stream(const Params& p, LAS unsigned char* lds, int l, int rs, int T, int h, int dir, int dvh) {
;     ...
;         { const int tt = w >> 1, ts0 = (w & 1) * 2; f32x4 pa = (f32x4){0.f, 0.f, 0.f, 0.f}, pb = pa;
;           bf16x8 gq_[KS], gk0[KS], gk1[KS];
; #pragma unroll
;           for (int ks = 0; ks < KS; ++ks) { gq_[ks] = ldfrag(Qs, QP, tt, ks, fr, fqx); gk0[ks] = ldfrag(Ks, QP, ts0, ks, fr, fqx); gk1[ks] = ldfrag(Ks, QP, ts0 + 1, ks, fr, fqx); }
;           __builtin_amdgcn_sched_barrier(0);
; #pragma unroll
;           for (int ks = 0; ks < KS; ++ks) { pa = MFMA16(gk0[ks], gq_[ks], pa); pb = MFMA16(gk1[ks], gq_[ks], pb); }
;           const int t = tt * 16 + fr, s0 = ts0 * 16 + fq * 4, s1 = s0 + 16;
;           u32x2 w0, w1;
;           w0.x = cvt_pk_bf16(t >= s0 ? pa[0] : 0.f, t >= s0 + 1 ? pa[1] : 0.f); w0.y = cvt_pk_bf16(t >= s0 + 2 ? pa[2] : 0.f, t >= s0 + 3 ? pa[3] : 0.f);
;           w1.x = cvt_pk_bf16(t >= s1 ? pb[0] : 0.f, t >= s1 + 1 ? pb[1] : 0.f); w1.y = cvt_pk_bf16(t >= s1 + 2 ? pb[2] : 0.f, t >= s1 + 3 ? pb[3] : 0.f);
;           *(LAS u32x2*)(Ps + t * TP + ((s0 * 2) ^ (gx << 4))) = w0; *(LAS u32x2*)(Ps + t * TP + ((s1 * 2) ^ (gx << 4))) = w1; }
; #pragma unroll
;         for (int ks = 0; ks < 2; ++ks) { bf16x8 ak[2], bv[DVW];
; #pragma unroll
;             for (int dki = 0; dki < 2; ++dki) ak[dki] = ldfrag(Kt, TP, tdk0 + dki, ks, fr, fqx);
; #pragma unroll
;             for (int dvi = 0; dvi < DVW; ++dvi) bv[dvi] = ldfrag(Vt, TP, tdv0 + dvi, ks, fr, fqx);
;             __builtin_amdgcn_sched_barrier(0);
; #pragma unroll
;             for (int dki = 0; dki < 2; ++dki)
; #pragma unroll
;                 for (int dvi = 0; dvi < DVW; ++dvi) U[dki * DVW + dvi] = MFMA16(ak[dki], bv[dvi], U[dki * DVW + dvi]);
;             __builtin_amdgcn_sched_barrier(0); }
;         LDS_BARRIER();
;         { const int tp = w >> 2, dp = w & 3; f32x4 o[4];
; #pragma unroll
;           for (int q = 0; q < 4; ++q) o[q] = (f32x4){0.f, 0.f, 0.f, 0.f};
; #pragma unroll
;           for (int kb = 0; kb < KS; kb += 2) { bf16x8 b[2][2], a[2][2];
; #pragma unroll
;               for (int k2 = 0; k2 < 2; ++k2)
; #pragma unroll
;                   for (int i2 = 0; i2 < 2; ++i2) { b[k2][i2] = ldfrag(Qs, QP, 2 * tp + i2, kb + k2, fr, fqx); a[k2][i2] = ldfrag(St, QP, 2 * dp + i2, kb + k2, fr, fqx); }
	v_add_u32_e32 v85, v94, v53
	v_add_u32_e32 v157, 0, v53
	v_add_u32_e32 v86, v54, v53
	v_add_u32_e32 v87, v55, v53
	ds_read_b128 v[42:45], v85
	ds_read_b128 v[46:49], v85 offset:64
	ds_read_b128 v[50:53], v86 offset:9216
	ds_read_b128 v[54:57], v86 offset:9280
	ds_read_b128 v[98:101], v87 offset:9216
	ds_read_b128 v[102:105], v87 offset:9280
	v_mul_f32_e32 v38, 0xc2800000, v38
	v_mul_f32_e32 v38, 0x3fb8aa3b, v38
	v_exp_f32_e32 v38, v38
	v_mov_b32_e32 v31, v177
	s_mov_b32 s8, 1
	v_readlane_b32 s77, v254, 28
	v_lshl_add_u64 v[32:33], s[0:1], 0, v[30:31]
	v_mov_b32_e32 v36, v34
	v_mov_b32_e32 v37, v34
	v_mov_b32_e32 v40, v38
	v_mov_b32_e32 v41, v38
	v_add_u32_e32 v154, s77, v70
	v_mul_u32_u24_e32 v156, 0x90, v97
	v_or_b32_e32 v35, s13, v95
	v_lshl_or_b32 v118, s11, 5, v95
	s_waitcnt lgkmcnt(0)
	v_mfma_f32_16x16x32_bf16 v[50:53], v[50:53], v[42:45], 0
	v_add_u32_e32 v93, v94, v93
	v_add_u32_e32 v94, v94, v106
	v_mad_u32_u24 v97, v97, s16, v157
	s_waitcnt lgkmcnt(1)
	v_mfma_f32_16x16x32_bf16 v[42:45], v[98:101], v[42:45], 0
	v_lshl_or_b32 v98, s60, 4, v95
	v_add_u32_e32 v95, v157, v39
	v_mul_u32_u24_e32 v39, 0x90, v98
	v_mfma_f32_16x16x32_bf16 v[50:53], v[54:57], v[46:49], v[50:53]
	s_waitcnt lgkmcnt(0)
	v_mfma_f32_16x16x32_bf16 v[42:45], v[102:105], v[46:49], v[42:45]
	v_mad_u32_u24 v102, v98, s16, v157
	s_nop 4
	v_cndmask_b32_e64 v50, v50, 0, s[42:43]
	v_cndmask_b32_e64 v51, 0, v51, s[44:45]
	v_cvt_pk_bf16_f32 v50, v50, v51
	v_cndmask_b32_e64 v51, v52, 0, s[46:47]
	v_cndmask_b32_e64 v42, v42, 0, s[50:51]
	v_cndmask_b32_e64 v43, v43, 0, s[52:53]
	v_cvt_pk_bf16_f32 v42, v42, v43
	v_cndmask_b32_e64 v43, v44, 0, s[54:55]
	v_cndmask_b32_e64 v52, v53, 0, s[48:49]
	v_cvt_pk_bf16_f32 v51, v51, v52
	v_cndmask_b32_e64 v44, v45, 0, s[56:57]
	v_cvt_pk_bf16_f32 v43, v43, v44
	ds_write_b64 v93, v[50:51] offset:64512
	ds_write_b64 v94, v[42:43] offset:64512
	ds_read_b128 v[42:45], v97 offset:36864
	ds_read_b128 v[46:49], v102 offset:36864
	ds_read_b128 v[50:53], v95 offset:18432
	ds_read_b128 v[54:57], v95 offset:20736
	s_waitcnt lgkmcnt(1)
	v_mfma_f32_16x16x32_bf16 v[98:101], v[42:45], v[50:53], 0
	s_waitcnt lgkmcnt(0)
	v_mfma_f32_16x16x32_bf16 v[42:45], v[42:45], v[54:57], 0
	v_mfma_f32_16x16x32_bf16 v[50:53], v[46:49], v[50:53], 0
	v_mfma_f32_16x16x32_bf16 v[46:49], v[46:49], v[54:57], 0
	ds_read_b128 v[54:57], v97 offset:36928
	ds_read_b128 v[102:105], v102 offset:36928
	ds_read_b128 v[106:109], v95 offset:18496
	ds_read_b128 v[110:113], v95 offset:20800
	s_waitcnt lgkmcnt(1)
	v_mfma_f32_16x16x32_bf16 v[114:117], v[54:57], v[106:109], v[98:101]
	s_waitcnt lgkmcnt(0)
	v_mfma_f32_16x16x32_bf16 v[54:57], v[54:57], v[110:113], v[42:45]
	v_mfma_f32_16x16x32_bf16 v[50:53], v[102:105], v[106:109], v[50:53]
	v_mfma_f32_16x16x32_bf16 v[44:47], v[102:105], v[110:113], v[46:49]
	s_nop 0
	v_mul_lo_u32 v42, v35, s16
	v_add_u32_e32 v97, v157, v42
	v_add_u32_e32 v42, 0x900, v42
	s_waitcnt lgkmcnt(0)
	s_barrier
	v_mad_u32_u24 v43, v118, s16, v157
	v_add_u32_e32 v98, v157, v42
	ds_read_b128 v[100:103], v97
	ds_read_b128 v[104:107], v43 offset:46080
	v_mul_u32_u24_e32 v112, 0x90, v118
	ds_read_b128 v[108:111], v98
	ds_read_b128 v[118:121], v43 offset:48384
	ds_read_b128 v[122:125], v97 offset:64
	ds_read_b128 v[126:129], v43 offset:46144
	ds_read_b128 v[130:133], v98 offset:64
	ds_read_b128 v[134:137], v43 offset:48448
	s_waitcnt lgkmcnt(6)
	v_mfma_f32_16x16x32_bf16 v[138:141], v[104:107], v[100:103], 0
	s_waitcnt lgkmcnt(4)
	v_mfma_f32_16x16x32_bf16 v[100:103], v[118:121], v[100:103], 0
	v_mfma_f32_16x16x32_bf16 v[104:107], v[104:107], v[108:111], 0
	v_mfma_f32_16x16x32_bf16 v[108:111], v[118:121], v[108:111], 0
	s_waitcnt lgkmcnt(0)
	v_mfma_f32_16x16x32_bf16 v[100:103], v[134:137], v[122:125], v[100:103]
	v_mfma_f32_16x16x32_bf16 v[104:107], v[126:129], v[130:133], v[104:107]
	v_mfma_f32_16x16x32_bf16 v[118:121], v[126:129], v[122:125], v[138:141]
	v_mfma_f32_16x16x32_bf16 v[108:111], v[134:137], v[130:133], v[108:111]
	ds_read_b128 v[122:125], v97 offset:64512
	ds_read_b128 v[126:129], v97 offset:64576
	ds_read_b128 v[130:133], v43 offset:18432
	ds_read_b128 v[134:137], v43 offset:18496
	ds_read_b128 v[138:141], v98 offset:64512
	ds_read_b128 v[142:145], v98 offset:64576
	ds_read_b128 v[146:149], v43 offset:20736
	ds_read_b128 v[150:153], v43 offset:20800
	s_waitcnt lgkmcnt(1)
	v_mfma_f32_16x16x32_bf16 v[100:103], v[146:149], v[122:125], v[100:103]
	v_mfma_f32_16x16x32_bf16 v[104:107], v[130:133], v[138:141], v[104:107]
	v_mfma_f32_16x16x32_bf16 v[118:121], v[130:133], v[122:125], v[118:121]
	v_mfma_f32_16x16x32_bf16 v[108:111], v[146:149], v[138:141], v[108:111]
	s_waitcnt lgkmcnt(0)
	v_mfma_f32_16x16x32_bf16 v[100:103], v[150:153], v[126:129], v[100:103]
	v_mfma_f32_16x16x32_bf16 v[104:107], v[134:137], v[142:145], v[104:107]
	v_mfma_f32_16x16x32_bf16 v[118:121], v[134:137], v[126:129], v[118:121]
	v_mfma_f32_16x16x32_bf16 v[108:111], v[150:153], v[142:145], v[108:111]
	s_lshl_b32 s11, s11, 6
	v_mul_lo_u32 v35, v35, s78
	s_add_i32 s11, s11, s77
	v_add_u32_e32 v35, s11, v35
	v_cvt_pk_bf16_f32 v42, v118, v119
	v_cvt_pk_bf16_f32 v43, v120, v121
	v_add_u32_e32 v99, v35, v155
	v_cvt_pk_bf16_f32 v48, v100, v101
	v_cvt_pk_bf16_f32 v49, v102, v103
	v_add_u32_e32 v35, 0x1100, v35
	ds_write2_b64 v99, v[42:43], v[48:49] offset1:4
	v_cvt_pk_bf16_f32 v42, v104, v105
	v_cvt_pk_bf16_f32 v43, v106, v107
	v_add_u32_e32 v100, v35, v155
	v_cvt_pk_bf16_f32 v48, v108, v109
	v_cvt_pk_bf16_f32 v49, v110, v111
	v_mul_f32_e32 v102, 0, v38
	ds_write2_b64 v100, v[42:43], v[48:49] offset1:4
	v_pk_fma_f32 v[42:43], v[34:35], v[46:47], v[102:103] op_sel_hi:[0,1,0]
	v_pk_fma_f32 v[44:45], v[34:35], v[44:45], v[102:103] op_sel_hi:[0,1,0]
	v_pk_fma_f32 v[46:47], v[34:35], v[52:53], v[102:103] op_sel_hi:[0,1,0]
	v_pk_fma_f32 v[48:49], v[34:35], v[50:51], v[102:103] op_sel_hi:[0,1,0]
	v_pk_fma_f32 v[50:51], v[34:35], v[56:57], v[102:103] op_sel_hi:[0,1,0]
	v_pk_fma_f32 v[52:53], v[34:35], v[54:55], v[102:103] op_sel_hi:[0,1,0]
	v_pk_fma_f32 v[54:55], v[34:35], v[116:117], v[102:103] op_sel_hi:[0,1,0]
	v_pk_fma_f32 v[56:57], v[34:35], v[114:115], v[102:103] op_sel_hi:[0,1,0]
	s_add_i32 s11, s19, 0xffffff40
	s_movk_i32 s14, 0x80
	v_add_u32_e32 v101, v154, v71
	v_add_u32_e32 v102, v157, v156
	v_add_u32_e32 v103, v157, v39
	v_add_u32_e32 v104, v157, v112
	v_readfirstlane_b32 s100, v230
	s_nop 3
	s_lshr_b32 s100, s100, 6
	s_cmp_ge_u32 s100, 4
	s_cbranch_scc0 .Lnoprio_b
	s_setprio 1
; template <int DK, bool IS_A, int NDV>
; __device__ __forceinline__ void mix_stream(const Params& p, LAS unsigned char* lds, int l, int rs, int T, int h, int dir, int dvh) {
;     ...
;         { const int tt = w >> 1, ts0 = (w & 1) * 2; f32x4 pa = (f32x4){0.f, 0.f, 0.f, 0.f}, pb = pa;
;           bf16x8 gq_[KS], gk0[KS], gk1[KS];
; #pragma unroll
;           for (int ks = 0; ks < KS; ++ks) { gq_[ks] = ldfrag(Qs, QP, tt, ks, fr, fqx); gk0[ks] = ldfrag(Ks, QP, ts0, ks, fr, fqx); gk1[ks] = ldfrag(Ks, QP, ts0 + 1, ks, fr, fqx); }
;           __builtin_amdgcn_sched_barrier(0);
; #pragma unroll
;           for (int ks = 0; ks < KS; ++ks) { pa = MFMA16(gk0[ks], gq_[ks], pa); pb = MFMA16(gk1[ks], gq_[ks], pb); }
;           const int t = tt * 16 + fr, s0 = ts0 * 16 + fq * 4, s1 = s0 + 16;
;           u32x2 w0, w1;
;           w0.x = cvt_pk_bf16(t >= s0 ? pa[0] : 0.f, t >= s0 + 1 ? pa[1] : 0.f); w0.y = cvt_pk_bf16(t >= s0 + 2 ? pa[2] : 0.f, t >= s0 + 3 ? pa[3] : 0.f);
;           w1.x = cvt_pk_bf16(t >= s1 ? pb[0] : 0.f, t >= s1 + 1 ? pb[1] : 0.f); w1.y = cvt_pk_bf16(t >= s1 + 2 ? pb[2] : 0.f, t >= s1 + 3 ? pb[3] : 0.f);
;           *(LAS u32x2*)(Ps + t * TP + ((s0 * 2) ^ (gx << 4))) = w0; *(LAS u32x2*)(Ps + t * TP + ((s1 * 2) ^ (gx << 4))) = w1; }
; #pragma unroll
;         for (int ks = 0; ks < 2; ++ks) { bf16x8 ak[2], bv[DVW];
; #pragma unroll
;             for (int dki = 0; dki < 2; ++dki) ak[dki] = ldfrag(Kt, TP, tdk0 + dki, ks, fr, fqx);
; #pragma unroll
;             for (int dvi = 0; dvi < DVW; ++dvi) bv[dvi] = ldfrag(Vt, TP, tdv0 + dvi, ks, fr, fqx);
;             __builtin_amdgcn_sched_barrier(0);
; #pragma unroll
;             for (int dki = 0; dki < 2; ++dki)
; #pragma unroll
;                 for (int dvi = 0; dvi < DVW; ++dvi) U[dki * DVW + dvi] = MFMA16(ak[dki], bv[dvi], U[dki * DVW + dvi]);
;             __builtin_amdgcn_sched_barrier(0); }
;         LDS_BARRIER();
;         { const int tp = w >> 2, dp = w & 3; f32x4 o[4];
; #pragma unroll
;           for (int q = 0; q < 4; ++q) o[q] = (f32x4){0.f, 0.f, 0.f, 0.f};
; #pragma unroll
;           for (int kb = 0; kb < KS; kb += 2) { bf16x8 b[2][2], a[2][2];
; #pragma unroll
;               for (int k2 = 0; k2 < 2; ++k2)
; #pragma unroll
;                   for (int i2 = 0; i2 < 2; ++i2) { b[k2][i2] = ldfrag(Qs, QP, 2 * tp + i2, kb + k2, fr, fqx); a[k2][i2] = ldfrag(St, QP, 2 * dp + i2, kb + k2, fr, fqx); }
.Lnoprio_b:
	s_branch .LBB0_165
.LBB0_164:
	s_waitcnt lgkmcnt(0)
	s_barrier
	ds_read_b128 v[106:109], v85
	ds_read_b128 v[110:113], v85 offset:64
	ds_read_b128 v[114:117], v86 offset:9216
	ds_read_b128 v[118:121], v86 offset:9280
	ds_read_b128 v[122:125], v87 offset:9216
	ds_read_b128 v[126:129], v87 offset:9280
	ds_read_b128 v[180:183], v102 offset:36864
	ds_read_b128 v[184:187], v103 offset:36864
	ds_read_b128 v[188:191], v95 offset:18432
	ds_read_b128 v[192:195], v95 offset:20736
	ds_read_b128 v[196:199], v102 offset:36928
	ds_read_b128 v[200:203], v103 offset:36928
	ds_read_b128 v[204:207], v95 offset:18496
	ds_read_b128 v[208:211], v95 offset:20800
	s_waitcnt lgkmcnt(11)
	v_mfma_f32_16x16x32_bf16 v[212:215], v[114:117], v[106:109], 0
	s_waitcnt lgkmcnt(9)
	v_mfma_f32_16x16x32_bf16 v[216:219], v[122:125], v[106:109], 0
	v_mfma_f32_16x16x32_bf16 v[212:215], v[118:121], v[110:113], v[212:215]
	s_waitcnt lgkmcnt(8)
	v_mfma_f32_16x16x32_bf16 v[216:219], v[126:129], v[110:113], v[216:219]
	s_waitcnt lgkmcnt(5)
	v_mfma_f32_16x16x32_bf16 v[122:125], v[180:183], v[188:191], 0
	s_waitcnt lgkmcnt(4)
	v_mfma_f32_16x16x32_bf16 v[106:109], v[180:183], v[192:195], 0
	v_mfma_f32_16x16x32_bf16 v[114:117], v[184:187], v[188:191], 0
	v_mfma_f32_16x16x32_bf16 v[110:113], v[184:187], v[192:195], 0
	s_waitcnt lgkmcnt(1)
	v_mfma_f32_16x16x32_bf16 v[122:125], v[196:199], v[204:207], v[122:125]
	s_waitcnt lgkmcnt(0)
	v_mfma_f32_16x16x32_bf16 v[106:109], v[196:199], v[208:211], v[106:109]
	v_mfma_f32_16x16x32_bf16 v[114:117], v[200:203], v[204:207], v[114:117]
	v_mfma_f32_16x16x32_bf16 v[110:113], v[200:203], v[208:211], v[110:113]
	ds_read_b128 v[118:121], v97
	ds_read_b128 v[126:129], v97 offset:64
	ds_read_b128 v[130:133], v104 offset:46080
	ds_read_b128 v[134:137], v104 offset:46144
	ds_read_b128 v[138:141], v97 offset:2304
	ds_read_b128 v[142:145], v97 offset:2368
	ds_read_b128 v[146:149], v104 offset:48384
	ds_read_b128 v[150:153], v104 offset:48448
	v_cndmask_b32_e64 v39, v212, 0, s[42:43]
	v_cndmask_b32_e64 v105, 0, v213, s[44:45]
	v_cvt_pk_bf16_f32 v220, v39, v105
	v_cndmask_b32_e64 v39, v214, 0, s[46:47]
	v_cndmask_b32_e64 v105, v215, 0, s[48:49]
	v_cvt_pk_bf16_f32 v221, v39, v105
	v_cndmask_b32_e64 v39, v216, 0, s[50:51]
	v_cndmask_b32_e64 v105, v217, 0, s[52:53]
	v_cvt_pk_bf16_f32 v222, v39, v105
	v_cndmask_b32_e64 v39, v218, 0, s[54:55]
	v_cndmask_b32_e64 v105, v219, 0, s[56:57]
	v_cvt_pk_bf16_f32 v223, v39, v105
	ds_write_b64 v93, v[220:221] offset:64512
	ds_write_b64 v94, v[222:223] offset:64512
	s_waitcnt lgkmcnt(7)
	v_mfma_f32_16x16x32_bf16 v[154:157], v[130:133], v[118:121], 0
	s_waitcnt lgkmcnt(3)
	v_mfma_f32_16x16x32_bf16 v[118:121], v[146:149], v[118:121], 0
	v_mfma_f32_16x16x32_bf16 v[130:133], v[130:133], v[138:141], 0
	v_mfma_f32_16x16x32_bf16 v[138:141], v[146:149], v[138:141], 0
	v_mfma_f32_16x16x32_bf16 v[146:149], v[134:137], v[126:129], v[154:157]
	s_waitcnt lgkmcnt(2)
	v_mfma_f32_16x16x32_bf16 v[118:121], v[150:153], v[126:129], v[118:121]
	v_mfma_f32_16x16x32_bf16 v[126:129], v[134:137], v[142:145], v[130:133]
	v_mfma_f32_16x16x32_bf16 v[130:133], v[150:153], v[142:145], v[138:141]
	s_waitcnt lgkmcnt(0)
	s_barrier
	ds_read_b128 v[134:137], v97 offset:64512
	s_nop 1
	ds_read_b128 v[138:141], v97 offset:64576
	ds_read_b128 v[142:145], v104 offset:18432
	ds_read_b128 v[150:153], v104 offset:18496
	ds_read_b128 v[154:157], v98 offset:64512
	ds_read_b128 v[158:161], v98 offset:64576
	ds_read_b128 v[162:165], v104 offset:20736
	ds_read_b128 v[166:169], v104 offset:20800
	s_waitcnt lgkmcnt(5)
	v_mfma_f32_16x16x32_bf16 v[146:149], v[142:145], v[134:137], v[146:149]
	s_waitcnt lgkmcnt(1)
	v_mfma_f32_16x16x32_bf16 v[118:121], v[162:165], v[134:137], v[118:121]
	v_mfma_f32_16x16x32_bf16 v[126:129], v[142:145], v[154:157], v[126:129]
	v_mfma_f32_16x16x32_bf16 v[130:133], v[162:165], v[154:157], v[130:133]
	v_mfma_f32_16x16x32_bf16 v[134:137], v[150:153], v[138:141], v[146:149]
	s_waitcnt lgkmcnt(0)
	v_mfma_f32_16x16x32_bf16 v[118:121], v[166:169], v[138:141], v[118:121]
	v_mfma_f32_16x16x32_bf16 v[126:129], v[150:153], v[158:161], v[126:129]
	v_mfma_f32_16x16x32_bf16 v[130:133], v[166:169], v[158:161], v[130:133]
	v_cvt_pk_bf16_f32 v118, v118, v119
	v_cvt_pk_bf16_f32 v119, v120, v121
	v_mov_b32_e32 v39, v38
	v_pk_mul_f32 v[108:109], v[34:35], v[108:109]
	v_pk_mul_f32 v[106:107], v[36:37], v[106:107]
	v_cvt_pk_bf16_f32 v134, v134, v135
	v_cvt_pk_bf16_f32 v135, v136, v137
	s_nop 2
	ds_write2_b64 v99, v[134:135], v[118:119] offset1:4
	v_cvt_pk_bf16_f32 v118, v126, v127
	v_cvt_pk_bf16_f32 v119, v128, v129
	v_cvt_pk_bf16_f32 v120, v130, v131
	v_cvt_pk_bf16_f32 v121, v132, v133
	v_pk_fma_f32 v[50:51], v[38:39], v[50:51], v[108:109]
	v_pk_fma_f32 v[52:53], v[40:41], v[52:53], v[106:107]
	v_pk_mul_f32 v[106:107], v[34:35], v[116:117]
	v_pk_mul_f32 v[108:109], v[36:37], v[114:115]
	ds_write2_b64 v100, v[118:119], v[120:121] offset1:4
	v_pk_mul_f32 v[118:119], v[34:35], v[124:125]
	v_pk_mul_f32 v[120:121], v[36:37], v[122:123]
	v_pk_fma_f32 v[46:47], v[38:39], v[46:47], v[106:107]
	v_pk_fma_f32 v[48:49], v[40:41], v[48:49], v[108:109]
	v_pk_mul_f32 v[106:107], v[34:35], v[112:113]
	v_pk_mul_f32 v[108:109], v[36:37], v[110:111]
	s_add_i32 s14, s14, 64
	s_sub_i32 s11, s11, 64
	v_pk_fma_f32 v[54:55], v[38:39], v[54:55], v[118:119]
	v_pk_fma_f32 v[56:57], v[40:41], v[56:57], v[120:121]
	v_pk_fma_f32 v[42:43], v[38:39], v[42:43], v[106:107]
	s_cmp_lg_u32 s10, s8
	v_pk_fma_f32 v[44:45], v[40:41], v[44:45], v[108:109]
	s_cbranch_scc0 .LBB0_169

; template <int DK, bool IS_A, int NDV>
; __device__ __forceinline__ void mix_stream(const Params& p, LAS unsigned char* lds, int l, int rs, int T, int h, int dir, int dvh) {
;     ...
;     __syncthreads();
;     MIX_FLUSH(N - 1);
;     __syncthreads();
.LBB0_169:
	s_setprio 0
	s_and_b64 s[8:9], vcc, exec
	s_cselect_b32 s8, s59, 0
	s_add_i32 s8, s8, s18
	s_ashr_i32 s9, s8, 31
	s_lshl_b64 s[8:9], s[8:9], 11
	s_add_u32 s0, s0, s8
	s_addc_u32 s1, s1, s9
	v_lshl_add_u64 v[8:9], s[0:1], 0, v[30:31]
	v_readlane_b32 s0, v254, 28
	s_waitcnt lgkmcnt(0)
	s_barrier
	v_add3_u32 v4, s0, v71, v70
	ds_read_b128 v[0:3], v4
	ds_read_b128 v[4:7], v4 offset:16
	s_mov_b64 s[0:1], 0
	s_mov_b32 s77, 0x3670000
	s_waitcnt lgkmcnt(1)
	global_store_dwordx4 v[8:9], v[0:3], off
	s_waitcnt lgkmcnt(0)
	global_store_dwordx4 v[8:9], v[4:7], off offset:16
	s_barrier
